# attention loop: K/V tile pointers advanced in SGPR pairs (scalar adds) instead of VGPR pairs, 6 fewer VALU per tile; next_free_sgpr 102
# speedup vs baseline: 1.0116x; 1.0051x over previous
; __device__ __forceinline__ int mk_tid() { int t = threadIdx.x; asm volatile("" : "+v"(t)); return t; }
; #define LAS __attribute__((address_space(3)))
; __device__ __forceinline__ void dattn_unit(LAS unsigned char* lds, int b, int h, int qb, const bf16* Q, const bf16* K, const bf16* V, bf16* YB, float lam, const float* subg, float oml, int tid) {
;     tid = mk_tid();
;     const int lane = tid & 63, w = __builtin_amdgcn_readfirstlane(tid >> 6), ql = lane & 31, hi = lane >> 5;
;     const LAS float* tab = (const LAS float*)(lds + AT_TAB);
;     const size_t rowb = (size_t)b * SEQ;
;     const int qmin = qb * 256 + w * 32, q = qmin + ql, qmax = qmin + 31;
;     LAS bf16x8* qs = (LAS bf16x8*)(lds + AT_QS) + w * 512 + lane;
; #pragma unroll
;     for (int mp = 0; mp < 2; ++mp)
; #pragma unroll
;         for (int ks = 0; ks < 4; ++ks) qs[(mp * 4 + ks) * 64] = *(const bf16x8*)(Q + (rowb + q) * 1024 + h * 128 + mp * 64 + ks * 16 + hi * 8);
;     f32x16 o[2][4];
; #pragma unroll
;     for (int mp = 0; mp < 2; ++mp)
; #pragma unroll
;         for (int cb = 0; cb < 4; ++cb) o[mp][cb] = f32x16{};
;     float mref[2] = {0.f, 0.f}, lsum[2] = {0.f, 0.f};
;     const int NT = 4 * qb + 4;
;     const bf16* kg = K + (rowb + (tid >> 3)) * 1024 + h * 128 + (tid & 7) * 8;
;     const bf16* vg = V + (rowb + (tid & 63)) * 1024 + h * 128 + (tid >> 6) * 16;
;     v4u kr0 = *(const v4u*)(kg), kr1 = *(const v4u*)(kg + 64), vr0 = *(const v4u*)(vg), vr1 = *(const v4u*)(vg + 8);
;     ...
;     AT_STAGE(0);
;     __syncthreads();
.LBB0_225:
	v_mov_b32_e32 v54, v211
	s_lshl_b32 s19, s35, 8
	v_ashrrev_i32_e32 v52, 6, v54
	v_ashrrev_i32_e32 v48, 3, v54
	v_readfirstlane_b32 s18, v52
	s_lshl_b32 s31, s18, 5
	v_ashrrev_i32_e32 v49, 31, v48
	v_and_b32_e32 v55, 31, v54
	s_add_i32 s31, s31, s19
	v_lshl_add_u64 v[32:33], s[6:7], 0, v[48:49]
	v_lshlrev_b32_e32 v34, 3, v54
	v_or_b32_e32 v178, s31, v55
	v_lshlrev_b64 v[32:33], 11, v[32:33]
	v_and_b32_e32 v34, 56, v34
	v_and_b32_e32 v53, 63, v54
	v_ashrrev_i32_e32 v179, 31, v178
	v_lshl_add_u64 v[32:33], s[10:11], 0, v[32:33]
	v_lshlrev_b32_e32 v180, 1, v34
	v_mov_b32_e32 v181, v209
	v_lshl_add_u64 v[0:1], s[6:7], 0, v[178:179]
	v_lshl_add_u64 v[36:37], v[32:33], 0, v[180:181]
	v_or_b32_e32 v32, s6, v53
	v_mov_b32_e32 v33, s7
	v_lshlrev_b32_e32 v34, 4, v52
	v_bfe_u32 v194, v54, 5, 1
	v_lshlrev_b64 v[0:1], 11, v[0:1]
	v_lshlrev_b64 v[32:33], 11, v[32:33]
	v_ashrrev_i32_e32 v35, 31, v34
	v_lshl_add_u64 v[176:177], s[8:9], 0, v[0:1]
	v_lshlrev_b32_e32 v208, 4, v194
	v_lshl_add_u64 v[32:33], s[20:21], 0, v[32:33]
	v_lshlrev_b64 v[50:51], 1, v[34:35]
	v_lshl_add_u64 v[28:29], v[176:177], 0, v[208:209]
	v_lshl_add_u64 v[44:45], v[32:33], 0, v[50:51]
	global_load_dwordx4 v[0:3], v[28:29], off
	global_load_dwordx4 v[4:7], v[28:29], off offset:32
	global_load_dwordx4 v[8:11], v[28:29], off offset:64
	global_load_dwordx4 v[12:15], v[28:29], off offset:96
	global_load_dwordx4 v[16:19], v[28:29], off offset:128
	global_load_dwordx4 v[20:23], v[28:29], off offset:160
	global_load_dwordx4 v[24:27], v[28:29], off offset:192
	s_nop 0
	global_load_dwordx4 v[28:31], v[28:29], off offset:224
	s_nop 0
	global_load_dwordx4 v[32:35], v[36:37], off
	s_nop 0
	global_load_dwordx4 v[36:39], v[36:37], off offset:128
	s_nop 0
	global_load_dwordx4 v[40:43], v[44:45], off
	s_nop 0
	global_load_dwordx4 v[44:47], v[44:45], off offset:16
	s_lshl_b32 s19, s35, 10
	s_or_b32 s56, s19, 0x300
	s_movk_i32 s19, 0x48
	s_lshl_b32 s18, s18, 13
	v_mul_lo_u32 v56, v48, s19
	s_movk_i32 s19, 0x480
	s_add_i32 s18, s18, 0
	v_mul_lo_u32 v57, v52, s19
	v_lshlrev_b32_e32 v195, 1, v53
	v_lshrrev_b32_e32 v58, 2, v53
	v_lshrrev_b32_e32 v59, 3, v53
	v_xor_b32_e32 v58, v58, v59
	v_and_b32_e32 v58, 1, v58
	v_mul_u32_u24_e32 v58, 24, v58
	v_xor_b32_e32 v195, v195, v58
	v_lshlrev_b32_e32 v52, 11, v53
	v_lshl_add_u32 v53, v53, 4, s18
	v_lshlrev_b32_e32 v196, 1, v56
	v_lshlrev_b32_e32 v197, 1, v57
	v_add_u32_e32 v189, 0x12400, v53
	v_mov_b32_e32 v53, v209
	v_mul_u32_u24_e32 v192, 0x90, v55
	v_add3_u32 v55, 0, v196, v180
	v_add3_u32 v56, 0, v197, v195
	v_lshlrev_b32_e32 v193, 4, v194
	s_or_b32 s35, s31, 31
	s_mov_b32 s57, 0
	v_mov_b32_e32 v179, 0
	s_movk_i32 s58, 0xb0
	v_mov_b32_e32 v181, 0
	v_mov_b32_e32 v190, 0
	v_mov_b32_e32 v191, 0
	s_mov_b32 s59, 0
	s_waitcnt vmcnt(11)
	ds_write_b128 v189, v[0:3]
	s_waitcnt vmcnt(10)
	ds_write_b128 v189, v[4:7] offset:1024
	s_waitcnt vmcnt(9)
	ds_write_b128 v189, v[8:11] offset:2048
	s_waitcnt vmcnt(8)
	ds_write_b128 v189, v[12:15] offset:3072
	s_waitcnt vmcnt(7)
	ds_write_b128 v189, v[16:19] offset:4096
	s_waitcnt vmcnt(6)
	ds_write_b128 v189, v[20:23] offset:5120
	s_waitcnt vmcnt(5)
	ds_write_b128 v189, v[24:27] offset:6144
	s_waitcnt vmcnt(4)
	ds_write_b128 v189, v[28:31] offset:7168
	s_waitcnt vmcnt(3)
	ds_write_b128 v55, v[32:35]
	s_waitcnt vmcnt(2)
	ds_write_b128 v55, v[36:39] offset:9216
	s_waitcnt vmcnt(1)
	ds_write_b16 v56, v40 offset:18432
	ds_write_b16_d16_hi v56, v40 offset:18576
	ds_write_b16 v56, v41 offset:18720
	ds_write_b16_d16_hi v56, v41 offset:18864
	ds_write_b16 v56, v42 offset:19008
	ds_write_b16_d16_hi v56, v42 offset:19152
	ds_write_b16 v56, v43 offset:19296
	ds_write_b16_d16_hi v56, v43 offset:19440
	s_waitcnt vmcnt(0)
	ds_write_b16 v56, v44 offset:19584
	ds_write_b16_d16_hi v56, v44 offset:19728
	ds_write_b16 v56, v45 offset:19872
	ds_write_b16_d16_hi v56, v45 offset:20016
	ds_write_b16 v56, v46 offset:20160
	ds_write_b16_d16_hi v56, v46 offset:20304
	ds_write_b16 v56, v47 offset:20448
	ds_write_b16_d16_hi v56, v47 offset:20592
	v_lshl_add_u64 v[0:1], v[52:53], 0, v[50:51]
	v_lshl_add_u64 v[182:183], s[44:45], 0, v[0:1]
	v_lshlrev_b64 v[0:1], 11, v[48:49]
	v_and_b32_e32 v2, 7, v54
	v_lshl_or_b32 v0, v2, 4, v0
	v_lshl_add_u64 v[184:185], s[44:45], 0, v[0:1]
	v_lshlrev_b32_e32 v0, 2, v178
	v_sub_u32_e32 v0, v208, v0
	v_mov_b32_e32 v14, v209
	v_mov_b32_e32 v15, v209
	v_add_u32_e32 v198, 0, v0
	v_mov_b32_e32 v0, v209
	v_mov_b32_e32 v1, v209
	v_mov_b32_e32 v2, v209
	v_mov_b32_e32 v3, v209
	v_mov_b32_e32 v4, v209
	v_mov_b32_e32 v5, v209
	v_mov_b32_e32 v6, v209
	v_mov_b32_e32 v7, v209
	v_mov_b32_e32 v8, v209
	v_mov_b32_e32 v9, v209
	v_mov_b32_e32 v10, v209
	v_mov_b32_e32 v11, v209
	v_mov_b32_e32 v12, v209
	v_mov_b32_e32 v13, v209
	v_mov_b64_e32 v[46:47], v[14:15]
	v_mov_b64_e32 v[78:79], v[14:15]
	v_mov_b64_e32 v[110:111], v[14:15]
	v_mov_b64_e32 v[30:31], v[14:15]
	v_mov_b64_e32 v[62:63], v[14:15]
	v_mov_b64_e32 v[94:95], v[14:15]
	v_mov_b64_e32 v[126:127], v[14:15]
	v_mov_b64_e32 v[44:45], v[12:13]
	v_mov_b64_e32 v[42:43], v[10:11]
	v_mov_b64_e32 v[40:41], v[8:9]
	v_mov_b64_e32 v[38:39], v[6:7]
	v_mov_b64_e32 v[36:37], v[4:5]
	v_mov_b64_e32 v[34:35], v[2:3]
	v_mov_b64_e32 v[32:33], v[0:1]
	v_mov_b64_e32 v[76:77], v[12:13]
	v_mov_b64_e32 v[74:75], v[10:11]
	v_mov_b64_e32 v[72:73], v[8:9]
	v_mov_b64_e32 v[70:71], v[6:7]
	v_mov_b64_e32 v[68:69], v[4:5]
	v_mov_b64_e32 v[66:67], v[2:3]
	v_mov_b64_e32 v[64:65], v[0:1]
	v_mov_b64_e32 v[108:109], v[12:13]
	v_mov_b64_e32 v[106:107], v[10:11]
	v_mov_b64_e32 v[104:105], v[8:9]
	v_mov_b64_e32 v[102:103], v[6:7]
	v_mov_b64_e32 v[100:101], v[4:5]
	v_mov_b64_e32 v[98:99], v[2:3]
	v_mov_b64_e32 v[96:97], v[0:1]
	v_mov_b64_e32 v[28:29], v[12:13]
	v_mov_b64_e32 v[26:27], v[10:11]
	v_mov_b64_e32 v[24:25], v[8:9]
	v_mov_b64_e32 v[22:23], v[6:7]
	v_mov_b64_e32 v[20:21], v[4:5]
	v_mov_b64_e32 v[18:19], v[2:3]
	v_mov_b64_e32 v[16:17], v[0:1]
	v_mov_b64_e32 v[60:61], v[12:13]
	v_mov_b64_e32 v[58:59], v[10:11]
	v_mov_b64_e32 v[56:57], v[8:9]
	v_mov_b64_e32 v[54:55], v[6:7]
	v_mov_b64_e32 v[52:53], v[4:5]
	v_mov_b64_e32 v[50:51], v[2:3]
	v_mov_b64_e32 v[48:49], v[0:1]
	v_mov_b64_e32 v[92:93], v[12:13]
	v_mov_b64_e32 v[90:91], v[10:11]
	v_mov_b64_e32 v[88:89], v[8:9]
	v_mov_b64_e32 v[86:87], v[6:7]
	v_mov_b64_e32 v[84:85], v[4:5]
	v_mov_b64_e32 v[82:83], v[2:3]
	v_mov_b64_e32 v[80:81], v[0:1]
	v_mov_b64_e32 v[124:125], v[12:13]
	v_mov_b64_e32 v[122:123], v[10:11]
	v_mov_b64_e32 v[120:121], v[8:9]
	v_mov_b64_e32 v[118:119], v[6:7]
	v_mov_b64_e32 v[116:117], v[4:5]
	v_mov_b64_e32 v[114:115], v[2:3]
	v_mov_b64_e32 v[112:113], v[0:1]
	s_add_u32 s98, s16, 0x1b020000
	s_addc_u32 s99, s17, 0
	s_add_u32 s100, s16, 0xb020000
	s_addc_u32 s101, s17, 0
	s_waitcnt lgkmcnt(0)
	s_barrier
	s_branch .LBB0_227

; #define LAS __attribute__((address_space(3)))
; __device__ __forceinline__ void dattn_unit(LAS unsigned char* lds, int b, int h, int qb, const bf16* Q, const bf16* K, const bf16* V, bf16* YB, float lam, const float* subg, float oml, int tid) {
;     ...
;     for (int t = 0; t < NT; ++t) {
;         if (t + 1 < NT) { const size_t adv = (size_t)(t + 1) * 64 * 1024; kr0 = *(const v4u*)(kg + adv); kr1 = *(const v4u*)(kg + adv + 64); vr0 = *(const v4u*)(vg + adv); vr1 = *(const v4u*)(vg + adv + 8); }
;         const LAS bf16* Ks = (const LAS bf16*)(lds + (t & 1) * AT_BUF + AT_KS); const LAS bf16* Vt = (const LAS bf16*)(lds + (t & 1) * AT_BUF + AT_VT);
;         const int kvbase = t * 64;
;         if (kvbase <= qmax) {
;     ...
;         if (t + 1 < NT) AT_STAGE((t + 1) & 1);
;         __syncthreads();
.LBB0_226:
	s_add_i32 s59, s59, 1
	s_bitcmp1_b32 s59, 0
	s_cselect_b32 s18, 0x9000, 0
	s_add_i32 s60, s18, 0
	v_add3_u32 v128, s60, v196, v180
	s_addk_i32 s57, 0x100
	s_add_i32 s58, s58, 64
	s_waitcnt vmcnt(3)
	ds_write_b128 v128, v[168:171]
	s_waitcnt vmcnt(2)
	ds_write_b128 v128, v[172:175] offset:9216
	v_add3_u32 v128, s60, v197, v195
	s_add_u32 s98, s98, s14
	s_addc_u32 s99, s99, s15
	s_add_u32 s100, s100, s14
	s_addc_u32 s101, s101, s15
	s_cmp_lg_u32 s56, s57
	s_waitcnt vmcnt(1)
	ds_write_b16 v128, v164 offset:18432
	ds_write_b16_d16_hi v128, v164 offset:18576
	ds_write_b16 v128, v165 offset:18720
	ds_write_b16_d16_hi v128, v165 offset:18864
	ds_write_b16 v128, v166 offset:19008
	ds_write_b16_d16_hi v128, v166 offset:19152
	ds_write_b16 v128, v167 offset:19296
	ds_write_b16_d16_hi v128, v167 offset:19440
	s_waitcnt vmcnt(0)
	ds_write_b16 v128, v160 offset:19584
	ds_write_b16_d16_hi v128, v160 offset:19728
	ds_write_b16 v128, v161 offset:19872
	ds_write_b16_d16_hi v128, v161 offset:20016
	ds_write_b16 v128, v162 offset:20160
	ds_write_b16_d16_hi v128, v162 offset:20304
	ds_write_b16 v128, v163 offset:20448
	ds_write_b16_d16_hi v128, v163 offset:20592
	s_waitcnt lgkmcnt(0)
	s_barrier
	s_cbranch_scc0 .LBB0_249
.LBB0_227:
	v_lshl_add_u64 v[128:129], v[184:185], 0, s[98:99]
	v_lshl_add_u64 v[130:131], v[182:183], 0, s[100:101]
	global_load_dwordx4 v[168:171], v[128:129], off
	global_load_dwordx4 v[172:175], v[128:129], off offset:128
	s_add_i32 s18, s58, 0xffffff50
	global_load_dwordx4 v[164:167], v[130:131], off
	global_load_dwordx4 v[160:163], v[130:131], off offset:16
	s_cmp_gt_i32 s18, s35
	s_cbranch_scc1 .LBB0_226
	s_bitcmp1_b32 s59, 0
	s_cselect_b32 s18, 0x9000, 0
	s_add_i32 s38, s18, 0
	v_add3_u32 v199, s38, v208, v192
	ds_read_b128 v[138:141], v199
	ds_read_b128 v[200:203], v199 offset:9216
	ds_read_b128 v[204:207], v189
	ds_read_b128 v[218:221], v189 offset:4096
	v_xor_b32_e32 v144, 0x80000000, v190
	v_xor_b32_e32 v128, 0x80000000, v191
	v_mov_b32_e32 v145, v144
	v_mov_b64_e32 v[146:147], v[144:145]
	v_mov_b64_e32 v[148:149], v[144:145]
	v_mov_b64_e32 v[150:151], v[144:145]
	v_mov_b64_e32 v[152:153], v[144:145]
	v_mov_b64_e32 v[154:155], v[144:145]
	v_mov_b64_e32 v[156:157], v[144:145]
	v_mov_b64_e32 v[158:159], v[144:145]
	v_mov_b32_e32 v129, v128
	v_mov_b64_e32 v[130:131], v[128:129]
	v_mov_b64_e32 v[132:133], v[128:129]
	v_mov_b64_e32 v[134:135], v[128:129]
	v_mov_b64_e32 v[136:137], v[128:129]
	ds_read_b128 v[222:225], v199 offset:32
	ds_read_b128 v[226:229], v199 offset:9248
	ds_read_b128 v[230:233], v189 offset:1024
	ds_read_b128 v[234:237], v189 offset:5120
	s_waitcnt lgkmcnt(5)
	v_mfma_f32_32x32x16_bf16 v[144:159], v[138:141], v[204:207], v[144:159]
	v_mov_b64_e32 v[142:143], v[128:129]
	v_mov_b64_e32 v[138:139], v[128:129]
	v_mov_b64_e32 v[140:141], v[128:129]
	s_sub_i32 s18, s58, 32
	s_cmp_le_i32 s18, s31
	s_waitcnt lgkmcnt(4)
	v_mfma_f32_32x32x16_bf16 v[128:143], v[200:203], v[218:221], v[128:143]
	ds_read_b128 v[200:203], v199 offset:64
	ds_read_b128 v[204:207], v199 offset:9280
	ds_read_b128 v[218:221], v189 offset:2048
	ds_read_b128 v[238:241], v189 offset:6144
	s_waitcnt lgkmcnt(5)
	v_mfma_f32_32x32x16_bf16 v[144:159], v[222:225], v[230:233], v[144:159]
	s_waitcnt lgkmcnt(4)
	v_mfma_f32_32x32x16_bf16 v[128:143], v[226:229], v[234:237], v[128:143]
	ds_read_b128 v[222:225], v199 offset:96
	ds_read_b128 v[226:229], v199 offset:9312
	ds_read_b128 v[230:233], v189 offset:3072
	ds_read_b128 v[234:237], v189 offset:7168
	s_waitcnt lgkmcnt(5)
	v_mfma_f32_32x32x16_bf16 v[144:159], v[200:203], v[218:221], v[144:159]
	s_cbranch_scc0 .Lqk_diag0
	s_waitcnt lgkmcnt(1)
	v_mfma_f32_32x32x16_bf16 v[144:159], v[222:225], v[230:233], v[144:159]
	v_add3_u32 v219, s38, v193, v192
	ds_read_b128 v[212:215], v219 offset:32256
	ds_read_b128 v[220:223], v219 offset:18432
	v_mfma_f32_32x32x16_bf16 v[128:143], v[204:207], v[238:241], v[128:143]
	s_waitcnt lgkmcnt(2)
	v_mfma_f32_32x32x16_bf16 v[128:143], v[226:229], v[234:237], v[128:143]
	ds_read_b128 v[228:231], v219 offset:23040
	ds_read_b128 v[232:235], v219 offset:23072
	ds_read_b128 v[236:239], v219 offset:27648
	ds_read_b128 v[240:243], v219 offset:27680
	s_nop 1
